# v12: + MLA V-fragment reads as 2x ds_read_b64 instead of ds_read2_b64, static s_setprio 1 for waves 4-7 in MLA phase
# speedup vs baseline: 1.0240x; 1.0046x over previous
.LBB0_2691:
	s_or_b64 exec, exec, s[10:11]
	s_cmpk_gt_i32 s3, 0x83f
	s_waitcnt lgkmcnt(0)
	s_barrier
	s_cbranch_scc1 .LBB0_2732
	v_readfirstlane_b32 s4, v146
	s_nop 1
	s_cmpk_lt_u32 s4, 0x100
	s_cbranch_scc1 .Lmla_prio_done
	s_setprio 1
.Lmla_prio_done:
	v_and_b32_e32 v4, 31, v146
	v_lshrrev_b32_e32 v0, 1, v146
	s_movk_i32 s2, 0x1e0
	v_and_or_b32 v153, v0, s2, v4
	v_add_u32_e32 v5, 0x200, v146
	s_movk_i32 s2, 0x100
	v_cmp_gt_u32_e64 s[10:11], s2, v146
	v_mul_u32_u24_e32 v7, 0x1556, v146
	v_mul_u32_u24_e32 v9, 0x1556, v5
	s_mov_b32 s2, 0x7060302
	v_lshrrev_b32_e32 v8, 16, v7
	v_lshrrev_b32_e32 v10, 16, v9
	v_perm_b32 v7, v9, v7, s2
	s_movk_i32 s4, 0x68
	v_mad_i32_i24 v5, v10, -12, v5
	v_pk_mul_lo_u16 v7, v7, s4 op_sel_hi:[1,0]
	v_bfe_u32 v1, v146, 5, 1
	v_and_b32_e32 v6, 56, v147
	v_lshlrev_b32_e32 v142, 3, v5
	v_lshrrev_b32_e32 v180, 16, v7
	v_lshlrev_b32_e32 v5, 4, v5
	v_lshlrev_b32_e32 v0, 3, v1
	v_lshl_add_u32 v181, v180, 1, v5
	v_lshlrev_b32_e32 v158, 1, v6
	v_mul_u32_u24_e32 v5, 0x68, v4
	v_lshlrev_b32_e32 v6, 4, v1
	v_lshlrev_b32_e32 v160, 2, v1
	v_mbcnt_hi_u32_b32 v1, -1, v145
	v_lshl_add_u32 v184, v5, 1, v6
	v_and_b32_e32 v5, 64, v1
	v_mov_b32_e32 v97, 0
	v_mul_u32_u24_e32 v96, 0x4200, v154
	v_mad_i32_i24 v9, v8, -12, v146
	v_mul_u32_u24_e32 v185, 0x48, v4
	v_xor_b32_e32 v4, 32, v1
	v_add_u32_e32 v5, 64, v5
	v_lshl_add_u64 v[2:3], s[12:13], 0, v[96:97]
	v_lshlrev_b32_e32 v138, 3, v9
	v_ashrrev_i32_e32 v143, 31, v142
	v_cmp_lt_i32_e32 vcc, v4, v5
	v_mov_b32_e32 v159, v97
	s_movk_i32 s2, 0xc00
	v_ashrrev_i32_e32 v139, 31, v138
	v_cndmask_b32_e32 v1, v1, v4, vcc
	v_lshl_add_u64 v[162:163], v[2:3], 0, v[158:159]
	v_lshlrev_b64 v[2:3], 1, v[142:143]
	v_and_b32_e32 v11, 0xfff8, v7
	v_lshlrev_b32_e32 v9, 4, v9
	v_mul_u32_u24_e32 v182, 0x48, v154
	v_lshlrev_b32_e32 v186, 2, v1
	v_and_b32_e32 v1, 7, v146
	v_mad_u64_u32 v[166:167], s[4:5], v10, s2, v[2:3]
	v_lshlrev_b64 v[2:3], 1, v[138:139]
	v_mul_hi_u32_u24_e32 v137, 0xc00, v8
	v_mul_u32_u24_e32 v136, 0xc00, v8
	v_mul_u32_u24_e32 v140, 0xc00, v10
	v_mov_b32_e32 v141, v97
	v_lshl_add_u32 v161, v11, 1, v9
	v_lshl_add_u32 v183, v182, 1, v158
	s_mov_b32 s39, 0
	v_lshl_or_b32 v159, v185, 1, v0
	v_lshl_or_b32 v164, v1, 4, v96
	v_mov_b32_e32 v165, v97
	v_mad_u64_u32 v[168:169], s[4:5], v8, s2, v[2:3]
	v_mov_b32_e32 v187, 0x2100
	v_mov_b64_e32 v[170:171], s[94:95]
	v_lshlrev_b32_e32 v172, 1, v0
	v_mov_b32_e32 v173, v97
	v_mov_b32_e32 v188, 0x108000
	v_mov_b32_e32 v189, 0xc0
	s_mov_b64 s[40:41], 0x100
	s_mov_b64 s[42:43], 0x60000
	v_lshlrev_b32_e32 v190, 1, v11
	s_mov_b32 s6, s3
	s_branch .LBB0_2694

.LBB0_2719:
	v_sub_f32_e32 v48, v48, v191
	v_exp_f32_e32 v193, v48
	v_sub_f32_e32 v48, v49, v191
	v_exp_f32_e32 v195, v48
	s_waitcnt lgkmcnt(3)
	v_mfma_f32_32x32x16_bf16 v[80:95], v[236:239], v[116:119], v[80:95]
	ds_read_b128 v[236:239], v227 offset:6720
	v_sub_f32_e32 v48, v50, v191
	v_exp_f32_e32 v196, v48
	v_sub_f32_e32 v48, v51, v191
	v_exp_f32_e32 v197, v48
	s_waitcnt lgkmcnt(3)
	v_mfma_f32_32x32x16_bf16 v[80:95], v[240:243], v[120:123], v[80:95]
	ds_read_b128 v[240:243], v227 offset:6752
	v_sub_f32_e32 v48, v52, v191
	v_exp_f32_e32 v199, v48
	v_sub_f32_e32 v48, v53, v191
	v_exp_f32_e32 v200, v48
	s_waitcnt lgkmcnt(3)
	v_mfma_f32_32x32x16_bf16 v[64:79], v[244:247], v[100:103], 0
	ds_read_b128 v[244:247], v227 offset:6784
	v_sub_f32_e32 v48, v54, v191
	v_exp_f32_e32 v201, v48
	v_sub_f32_e32 v48, v55, v191
	v_exp_f32_e32 v202, v48
	s_waitcnt lgkmcnt(3)
	v_mfma_f32_32x32x16_bf16 v[64:79], v[248:251], v[104:107], v[64:79]
	ds_read_b128 v[248:251], v227 offset:6816
	v_sub_f32_e32 v48, v56, v191
	v_exp_f32_e32 v203, v48
	v_sub_f32_e32 v48, v57, v191
	v_exp_f32_e32 v204, v48
	s_waitcnt lgkmcnt(3)
	v_mfma_f32_32x32x16_bf16 v[64:79], v[236:239], v[108:111], v[64:79]
	v_sub_f32_e32 v48, v58, v191
	v_exp_f32_e32 v205, v48
	v_sub_f32_e32 v48, v59, v191
	v_sub_f32_e32 v32, v32, v191
	s_waitcnt lgkmcnt(2)
	v_mfma_f32_32x32x16_bf16 v[64:79], v[240:243], v[112:115], v[64:79]
	s_mul_i32 s20, s12, 0x2400
	v_exp_f32_e32 v206, v48
	v_sub_f32_e32 v48, v60, v191
	v_exp_f32_e32 v211, v32
	v_sub_f32_e32 v32, v33, v191
	s_waitcnt lgkmcnt(1)
	v_mfma_f32_32x32x16_bf16 v[64:79], v[244:247], v[116:119], v[64:79]
	v_lshlrev_b32_e32 v33, 1, v185
	v_lshlrev_b32_e32 v96, 1, v160
	v_exp_f32_e32 v207, v48
	v_sub_f32_e32 v48, v61, v191
	s_waitcnt lgkmcnt(0)
	v_mfma_f32_32x32x16_bf16 v[64:79], v[248:251], v[120:123], v[64:79]
	v_add3_u32 v52, s20, v33, v96
	v_exp_f32_e32 v208, v48
	v_sub_f32_e32 v48, v62, v191
	v_add_u32_e32 v58, 0xa800, v52
	v_exp_f32_e32 v209, v48
	v_sub_f32_e32 v48, v63, v191
	v_add_u32_e32 v56, 0x9800, v52
	ds_read_b64 v[52:53], v58 offset:1536
	ds_read_b64 v[54:55], v58 offset:1552
	v_exp_f32_e32 v210, v48
	ds_read_b64 v[48:49], v56 offset:1024
	ds_read_b64 v[50:51], v56 offset:1040
	v_sub_f32_e32 v36, v36, v191
	v_exp_f32_e32 v212, v32
	v_sub_f32_e32 v32, v34, v191
	v_exp_f32_e32 v215, v36
	v_sub_f32_e32 v36, v37, v191
	v_exp_f32_e32 v213, v32
	v_sub_f32_e32 v57, v35, v191
	v_cvt_pk_bf16_f32 v32, v193, v195
	v_cvt_pk_bf16_f32 v33, v196, v197
	v_cvt_pk_bf16_f32 v34, v199, v200
	v_cvt_pk_bf16_f32 v35, v201, v202
	v_exp_f32_e32 v216, v36
	v_sub_f32_e32 v36, v38, v191
	s_waitcnt lgkmcnt(2)
	v_mfma_f32_32x32x16_bf16 v[0:15], v[52:55], v[32:35], v[0:15]
	v_exp_f32_e32 v217, v36
	v_sub_f32_e32 v52, v39, v191
	ds_read_b64 v[36:37], v58 offset:1568
	ds_read_b64 v[38:39], v58 offset:1584
	v_sub_f32_e32 v40, v40, v191
	v_exp_f32_e32 v214, v57
	v_exp_f32_e32 v218, v52
	v_exp_f32_e32 v219, v40
	s_waitcnt lgkmcnt(2)
	v_mfma_f32_32x32x16_bf16 v[16:31], v[48:51], v[32:35], v[16:31]
	ds_read_b64 v[48:49], v56 offset:1056
	ds_read_b64 v[50:51], v56 offset:1072
	v_cvt_pk_bf16_f32 v32, v203, v204
	v_cvt_pk_bf16_f32 v33, v205, v206
	v_cvt_pk_bf16_f32 v34, v207, v208
	v_cvt_pk_bf16_f32 v35, v209, v210
	v_sub_f32_e32 v40, v41, v191
	v_exp_f32_e32 v220, v40
	s_waitcnt lgkmcnt(2)
	v_mfma_f32_32x32x16_bf16 v[0:15], v[36:39], v[32:35], v[0:15]
	ds_read_b64 v[36:37], v58 offset:1600
	ds_read_b64 v[38:39], v58 offset:1616
	v_sub_f32_e32 v40, v42, v191
	v_exp_f32_e32 v221, v40
	v_sub_f32_e32 v40, v43, v191
	v_exp_f32_e32 v222, v40
	v_sub_f32_e32 v40, v44, v191
	v_exp_f32_e32 v223, v40
	s_waitcnt lgkmcnt(2)
	v_mfma_f32_32x32x16_bf16 v[16:31], v[48:51], v[32:35], v[16:31]
	ds_read_b64 v[48:49], v56 offset:1088
	ds_read_b64 v[50:51], v56 offset:1104
	v_cvt_pk_bf16_f32 v32, v211, v212
	v_cvt_pk_bf16_f32 v33, v213, v214
	v_cvt_pk_bf16_f32 v34, v215, v216
	v_cvt_pk_bf16_f32 v35, v217, v218
	v_sub_f32_e32 v40, v45, v191
	v_exp_f32_e32 v224, v40
	ds_read_b64 v[40:41], v56 offset:1120
	ds_read_b64 v[42:43], v56 offset:1136
	s_waitcnt lgkmcnt(4)
	v_mfma_f32_32x32x16_bf16 v[0:15], v[36:39], v[32:35], v[0:15]
	ds_read_b64 v[36:37], v58 offset:1632
	ds_read_b64 v[38:39], v58 offset:1648
	v_sub_f32_e32 v44, v46, v191
	v_exp_f32_e32 v225, v44
	s_add_i32 s4, s16, -4
	s_cmp_ge_u32 s4, s9
	s_waitcnt lgkmcnt(0)
	s_barrier
	v_mfma_f32_32x32x16_bf16 v[16:31], v[48:51], v[32:35], v[16:31]
	v_sub_f32_e32 v32, v47, v191
	v_exp_f32_e32 v226, v32
	v_cvt_pk_bf16_f32 v32, v219, v220
	v_cvt_pk_bf16_f32 v33, v221, v222
	v_cvt_pk_bf16_f32 v34, v223, v224
	v_cvt_pk_bf16_f32 v35, v225, v226
	s_nop 1
	v_mfma_f32_32x32x16_bf16 v[16:31], v[40:43], v[32:35], v[16:31]
	v_mfma_f32_32x32x16_bf16 v[0:15], v[36:39], v[32:35], v[0:15]
	s_cbranch_scc1 .LBB0_2726
	s_mul_i32 s21, s12, 0x3400
	v_add3_u32 v32, s21, v190, v198
	s_waitcnt vmcnt(1)
	ds_write_b128 v32, v[128:131]
	s_and_saveexec_b64 s[4:5], s[10:11]
	v_lshlrev_b32_e32 v32, 1, v180
	v_lshlrev_b32_e32 v33, 1, v142
	v_add3_u32 v32, s21, v32, v33
	ds_write_b128 v32, v[124:127]
	s_or_b64 exec, exec, s[4:5]
	v_lshlrev_b32_e32 v32, 1, v182
	v_add3_u32 v32, s20, v32, v158
	s_cmp_ge_u32 s16, s8
	s_waitcnt vmcnt(0)
	ds_write_b128 v32, v[132:135] offset:39936
	s_cbranch_scc1 .LBB0_2726
	v_lshl_add_u64 v[32:33], s[90:91], 0, v[178:179]
	v_add_co_u32_e32 v32, vcc, 0x159c0000, v32
	s_nop 1
	v_addc_co_u32_e32 v33, vcc, 0, v33, vcc
	global_load_dwordx4 v[128:131], v[32:33], off
	s_and_saveexec_b64 s[4:5], s[10:11]
	s_cbranch_execz .LBB0_2725
	v_lshl_add_u64 v[32:33], s[90:91], 0, v[176:177]
	v_add_co_u32_e32 v32, vcc, 0x159c0000, v32
	s_nop 1
	v_addc_co_u32_e32 v33, vcc, 0, v33, vcc
	global_load_dwordx4 v[124:127], v[32:33], off

.LBB0_2730:
	v_sub_f32_e32 v80, v80, v191
	v_exp_f32_e32 v80, v80
	v_sub_f32_e32 v81, v81, v191
	v_sub_f32_e32 v82, v82, v191
	v_exp_f32_e32 v81, v81
	v_exp_f32_e32 v82, v82
	v_sub_f32_e32 v83, v83, v191
	v_sub_f32_e32 v84, v84, v191
	v_exp_f32_e32 v83, v83
	v_exp_f32_e32 v201, v84
	v_sub_f32_e32 v84, v85, v191
	v_sub_f32_e32 v64, v64, v191
	v_exp_f32_e32 v202, v84
	v_sub_f32_e32 v84, v86, v191
	v_sub_f32_e32 v86, v88, v191
	v_sub_f32_e32 v88, v90, v191
	v_sub_f32_e32 v90, v92, v191
	v_sub_f32_e32 v92, v94, v191
	v_exp_f32_e32 v94, v64
	v_sub_f32_e32 v64, v65, v191
	v_add_f32_e32 v193, 0, v80
	v_exp_f32_e32 v203, v84
	v_sub_f32_e32 v84, v87, v191
	v_sub_f32_e32 v87, v89, v191
	v_sub_f32_e32 v89, v91, v191
	v_sub_f32_e32 v91, v93, v191
	v_sub_f32_e32 v93, v95, v191
	v_exp_f32_e32 v95, v64
	v_sub_f32_e32 v64, v66, v191
	s_mul_i32 s4, s13, 0x2400
	v_add_f32_e32 v195, 0, v81
	v_add_f32_e32 v193, v82, v193
	v_exp_f32_e32 v196, v64
	v_sub_f32_e32 v64, v67, v191
	v_add_f32_e32 v195, v83, v195
	v_exp_f32_e32 v204, v84
	v_add_f32_e32 v84, v201, v193
	v_exp_f32_e32 v197, v64
	v_sub_f32_e32 v64, v68, v191
	v_add_u32_e32 v193, s4, v159
	v_add_f32_e32 v85, v202, v195
	v_exp_f32_e32 v198, v64
	v_sub_f32_e32 v64, v69, v191
	v_add_u32_e32 v195, 0x9800, v193
	v_exp_f32_e32 v199, v64
	ds_read_b64 v[64:65], v195 offset:1024
	ds_read_b64 v[66:67], v195 offset:1040
	v_sub_f32_e32 v68, v70, v191
	v_add_u32_e32 v193, 0xa800, v193
	v_exp_f32_e32 v200, v68
	v_sub_f32_e32 v205, v71, v191
	v_cvt_pk_bf16_f32 v68, v80, v81
	v_cvt_pk_bf16_f32 v69, v82, v83
	v_cvt_pk_bf16_f32 v70, v201, v202
	v_cvt_pk_bf16_f32 v71, v203, v204
	ds_read_b64 v[80:81], v193 offset:1536
	ds_read_b64 v[82:83], v193 offset:1552
	v_add_f32_e32 v84, v203, v84
	s_waitcnt lgkmcnt(2)
	v_mfma_f32_32x32x16_bf16 v[16:31], v[64:67], v[68:71], v[16:31]
	v_sub_f32_e32 v64, v72, v191
	v_exp_f32_e32 v202, v64
	v_sub_f32_e32 v64, v73, v191
	v_exp_f32_e32 v203, v64
	ds_read_b64 v[64:65], v195 offset:1056
	ds_read_b64 v[66:67], v195 offset:1072
	v_exp_f32_e32 v86, v86
	v_exp_f32_e32 v87, v87
	v_exp_f32_e32 v88, v88
	v_exp_f32_e32 v89, v89
	v_exp_f32_e32 v90, v90
	v_exp_f32_e32 v91, v91
	v_exp_f32_e32 v92, v92
	v_exp_f32_e32 v93, v93
	v_sub_f32_e32 v72, v74, v191
	s_waitcnt lgkmcnt(2)
	v_mfma_f32_32x32x16_bf16 v[0:15], v[80:83], v[68:71], v[0:15]
	v_exp_f32_e32 v80, v72
	v_sub_f32_e32 v81, v75, v191
	ds_read_b64 v[72:73], v193 offset:1568
	ds_read_b64 v[74:75], v193 offset:1584
	v_cvt_pk_bf16_f32 v68, v86, v87
	v_cvt_pk_bf16_f32 v69, v88, v89
	v_cvt_pk_bf16_f32 v70, v90, v91
	v_cvt_pk_bf16_f32 v71, v92, v93
	v_exp_f32_e32 v201, v205
	v_add_f32_e32 v85, v204, v85
	s_waitcnt lgkmcnt(2)
	v_mfma_f32_32x32x16_bf16 v[16:31], v[64:67], v[68:71], v[16:31]
	v_sub_f32_e32 v64, v76, v191
	v_exp_f32_e32 v76, v64
	v_sub_f32_e32 v64, v77, v191
	v_exp_f32_e32 v77, v64
	ds_read_b64 v[64:65], v195 offset:1088
	ds_read_b64 v[66:67], v195 offset:1104
	v_sub_f32_e32 v78, v78, v191
	v_sub_f32_e32 v79, v79, v191
	s_waitcnt lgkmcnt(2)
	v_mfma_f32_32x32x16_bf16 v[0:15], v[72:75], v[68:71], v[0:15]
	ds_read_b64 v[72:73], v193 offset:1600
	ds_read_b64 v[74:75], v193 offset:1616
	v_cvt_pk_bf16_f32 v68, v94, v95
	v_cvt_pk_bf16_f32 v69, v196, v197
	v_cvt_pk_bf16_f32 v70, v198, v199
	v_cvt_pk_bf16_f32 v71, v200, v201
	v_exp_f32_e32 v81, v81
	v_exp_f32_e32 v78, v78
	s_waitcnt lgkmcnt(2)
	v_mfma_f32_32x32x16_bf16 v[16:31], v[64:67], v[68:71], v[16:31]
	v_add_f32_e64 v64, v86, v84
	v_add_f32_e64 v65, v87, v85
	v_exp_f32_e32 v79, v79
	v_pk_add_f32 v[64:65], v[88:89], v[64:65]
	s_add_i32 s16, s16, 2
	v_pk_add_f32 v[64:65], v[90:91], v[64:65]
	v_lshl_add_u64 v[98:99], v[98:99], 0, s[40:41]
	v_pk_add_f32 v[64:65], v[92:93], v[64:65]
	s_waitcnt lgkmcnt(0)
	v_mfma_f32_32x32x16_bf16 v[0:15], v[72:75], v[68:71], v[0:15]
	v_add_f32_e64 v82, v94, v64
	v_add_f32_e64 v83, v95, v65
	ds_read_b64 v[64:65], v195 offset:1120
	ds_read_b64 v[66:67], v195 offset:1136
	ds_read_b64 v[72:73], v193 offset:1632
	ds_read_b64 v[74:75], v193 offset:1648
	v_add_f32_e64 v68, v196, v82
	v_add_f32_e64 v69, v197, v83
	v_cvt_pk_bf16_f32 v70, v76, v77
	v_pk_add_f32 v[82:83], v[198:199], v[68:69]
	v_cvt_pk_bf16_f32 v68, v202, v203
	v_cvt_pk_bf16_f32 v69, v80, v81
	v_cvt_pk_bf16_f32 v71, v78, v79
	v_lshl_add_u64 v[176:177], v[176:177], 0, s[42:43]
	s_cmp_ge_u32 s18, s8
	s_waitcnt lgkmcnt(2)
	v_mfma_f32_32x32x16_bf16 v[16:31], v[64:67], v[68:71], v[16:31]
	v_add_f32_e64 v64, v200, v82
	v_add_f32_e64 v65, v201, v83
	v_lshl_add_u64 v[178:179], v[178:179], 0, s[42:43]
	v_add_f32_e64 v64, v202, v64
	v_add_f32_e64 v65, v203, v65
	v_pk_add_f32 v[64:65], v[80:81], v[64:65]
	s_nop 0
	v_pk_add_f32 v[64:65], v[76:77], v[64:65]
	s_waitcnt lgkmcnt(0)
	v_mfma_f32_32x32x16_bf16 v[0:15], v[72:75], v[68:71], v[0:15]
	v_add_f32_e64 v64, v78, v64
	v_add_f32_e64 v65, v79, v65
	v_add_f32_e32 v64, v64, v65
	v_add_f32_e32 v192, v192, v64
	s_cbranch_scc1 .LBB0_2693
	s_mov_b32 s4, s13
	s_mov_b32 s13, s12
	s_mov_b32 s12, s17
	s_branch .LBB0_2710
.LBB0_2732:
	s_setprio 0
	s_waitcnt vmcnt(0)
	s_barrier
	s_mov_b64 s[0:1], exec
	v_readlane_b32 s4, v254, 2
	v_readlane_b32 s5, v254, 3
	s_and_b64 s[4:5], s[0:1], s[4:5]
	s_mov_b64 exec, s[4:5]
	s_cbranch_execz .LBB0_2784
	v_mov_b32_e32 v0, 0x25f80
	s_waitcnt vmcnt(0) expcnt(0) lgkmcnt(0)
	ds_read_b32 v2, v0
	v_mov_b32_e32 v0, 0x25f84
	ds_read_b32 v0, v0
	s_waitcnt lgkmcnt(1)
	v_cmp_ne_u32_e32 vcc, 0, v2
	s_cbranch_vccnz .LBB0_2748
	s_add_u32 s10, s90, 0xe0200
	s_addc_u32 s11, s91, 0
	s_add_u32 s12, s90, 0xe0400
	s_addc_u32 s13, s91, 0
	s_add_u32 s14, s90, 0xe0500
	s_addc_u32 s15, s91, 0
	s_add_u32 s16, s90, 0xe0600
	s_addc_u32 s17, s91, 0
	s_add_u32 s18, s90, 0xe0700
	s_addc_u32 s19, s91, 0
	s_add_u32 s20, s90, 0xe0800
	s_addc_u32 s21, s91, 0
	s_add_u32 s22, s90, 0xe0900
	s_addc_u32 s23, s91, 0
	s_add_u32 s24, s90, 0xe0a00
	s_addc_u32 s25, s91, 0
	s_add_u32 s26, s90, 0xe0b00
	s_addc_u32 s27, s91, 0
	s_add_u32 s38, s90, 0xe0c00
	s_addc_u32 s39, s91, 0
	s_add_u32 s40, s90, 0xe0d00
	s_addc_u32 s41, s91, 0
	s_add_u32 s42, s90, 0xe0e00
	s_addc_u32 s43, s91, 0
	s_add_u32 s44, s90, 0xe0f00
	s_addc_u32 s45, s91, 0
	s_add_u32 s46, s90, 0xe1000
	s_addc_u32 s47, s91, 0
	s_add_u32 s48, s90, 0xe1100
	s_addc_u32 s49, s91, 0
	s_add_u32 s50, s90, 0xe1200
	v_readlane_b32 s2, v254, 4
	s_addc_u32 s51, s91, 0
	s_mul_i32 s2, s83, s2
	s_add_u32 s54, s90, 0xe1300
	s_mul_i32 s2, s2, s82
	s_addc_u32 s55, s91, 0
	s_mov_b32 s6, 1
	v_mov_b32_e32 v16, 0
	s_branch .LBB0_2736
